# v19 with hipcc's per-segment s_setprio flips in the GEMM K-loops removed and one static s_setprio 1 for the wr==1 wave group (waves 4-7) per GEMM phase, reset at phase end
# speedup vs baseline: 1.0008x; 1.0008x over previous
; #define LAS3 __attribute__((address_space(3)))
; DI unsigned xb_xcc_id() { return (unsigned)__builtin_amdgcn_s_getreg((3 << 11) | 20) & 0xFu; }
; DI void xcd_barrier(unsigned* bar, volatile LAS3 unsigned* st) {
;   asm volatile("s_waitcnt vmcnt(0)" ::: "memory");
;   __syncthreads();
;   if (threadIdx.x == 0) {
;     const unsigned x = xb_xcc_id();
;     __builtin_amdgcn_s_waitcnt(0);
;     unsigned nloc = st[0], nx = st[1];
;     if (nloc == 0u) { xcd_barrier_complete(bar, x, nloc, nx); st[0] = nloc; st[1] = nx; }
; __global__ void __launch_bounds__(512, 2) mega(Params p, int ph_lo, int ph_hi) {
;     ...
;   for (int ph = ph_lo; ph < ph_hi; ++ph) {
;     ...
;     if (ph + 1 < ph_hi) { if (ph_hi > 1000) cg::this_grid().sync(); else xcd_barrier(p.bar, bst); }
.LBB0_51:
	s_setprio 0
	s_add_i32 s76, s76, 1
	s_cmp_ge_i32 s76, s77
	s_mov_b64 s[0:1], -1
	s_cbranch_scc1 .LBB0_12
	v_readlane_b32 s6, v254, 26
	v_readlane_b32 s7, v254, 27
	s_and_b64 vcc, exec, s[6:7]
	s_cbranch_vccz .LBB0_456
	s_waitcnt vmcnt(0)
	s_waitcnt lgkmcnt(0)
	s_barrier
	s_mov_b64 s[0:1], exec
	v_readlane_b32 s6, v255, 26
	v_readlane_b32 s7, v255, 27
	s_and_b64 s[6:7], s[0:1], s[6:7]
	s_mov_b64 exec, s[6:7]
	s_cbranch_execz .LBB0_455
	v_readlane_b32 s6, v255, 24
	s_getreg_b32 s2, hwreg(HW_REG_XCC_ID, 0, 4)
	s_waitcnt vmcnt(0) expcnt(0) lgkmcnt(0)
	v_mov_b32_e32 v0, s6
	ds_read_b32 v3, v0
	v_readlane_b32 s6, v255, 25
	s_and_b32 s2, s2, 15
	s_waitcnt lgkmcnt(0)
	v_cmp_ne_u32_e32 vcc, 0, v3
	v_mov_b32_e32 v0, s6
	ds_read_b32 v2, v0
	s_cbranch_vccnz .LBB0_141
	s_mov_b32 s12, 1
	s_branch .LBB0_99

; DI int opaque_tid() { int t = threadIdx.x; asm volatile("" : "+v"(t)); return t; }
; #define PG8_STAGE(bufoff, gbase, voff) do { _Pragma("unroll") for (int _i = 0; _i < 2; ++_i) \
;     __builtin_amdgcn_global_load_lds((const unsigned*)((const char*)(gbase) + (voff)[_i]), (PG8_LAS unsigned*)(lds + (bufoff) + ldsw + _i * 8192), 16, 0, 0); } while (0)
; #define PG8_BAR __builtin_amdgcn_s_barrier()
; template <class Epi>
; DI void gemm_phase(PG8_LAS unsigned char* lds, const Gemm g, const StaticOrder& S, const Epi& E) {
;   const int tid = opaque_tid(), wid = __builtin_amdgcn_readfirstlane(tid >> 6), lane = tid & 63, wr = wid >> 2, wc = wid & 3, fr = lane & 15, fq = lane >> 4;
;   const int K = g.K, nt = K / BK, lda = g.lda;
;   unsigned voffA[2], voffB[2];
; #pragma unroll
;   for (int i = 0; i < 2; ++i) { int R, C; stage_rc(tid * 16 + i * 8192, R, C); const int Rb = Epi::PERM ? ((R & ~31) + perm32(R & 31)) : R;
;     voffA[i] = (unsigned)(R * lda + C) * 2u; voffB[i] = (unsigned)(Rb * K + C) * 2u; }
;   const size_t kstep = (size_t)(BK * 2);
;   const size_t hstepA = (size_t)HALF * lda * 2, hstepB = (size_t)HALF * K * 2;
;   const size_t tstepA = 2 * hstepA, tstepB = 2 * hstepB;
;   const unsigned ldsw = (unsigned)wid * 1024u;
;   const int aoff = lds_byte(wr * 64 + fr, fq * 8), boff = lds_byte(wc * 32 + fr, fq * 8);
;     ...
;   Unit cur, nxt; int ui = 0;
;   if (!S.next(0, cur)) return;
;   f32x4 acc[2][2][4][2];
; #pragma unroll
;   for (int a = 0; a < 2; ++a)
; #pragma unroll
;     for (int b = 0; b < 2; ++b)
; #pragma unroll
;       for (int m = 0; m < 4; ++m)
; #pragma unroll
;         for (int n = 0; n < 2; ++n) acc[a][b][m][n] = (f32x4){0.f, 0.f, 0.f, 0.f};
;   bf16x8 At[4][2], B0[2][2], B1[2][2];
;   const char* cA = (const char*)g.A + (size_t)cur.pm * tstepA; const char* cB = (const char*)g.Bt + (size_t)cur.pn * tstepB;
;   PG8_STAGE(PG8_SB(0, 0), cB, voffB); PG8_STAGE(PG8_SA(0, 0), cA, voffA); PG8_STAGE(PG8_SB(0, 1), cB + hstepB, voffB); PG8_STAGE(PG8_SA(0, 1), cA + hstepA, voffA);
;   if (wr == 1) PG8_BAR;
; __global__ void __launch_bounds__(512, 2) mega(Params p, int ph_lo, int ph_hi) {
;     ...
;         const int M = (layer < 3) ? TT : TL;
;         const int goff = isA ? 1536 : 3072;
;         gemm_phase<EPI_OUT>(p, p.qkvg + goff, NW, (isA ? p.wt_a_out : p.wt_b_out) + (size_t)jl * 1024 * 1024, M, 1024, smem);
.LBB0_107:
	v_readlane_b32 s0, v255, 46
	s_cmp_lt_i32 s0, 3
	s_mov_b32 s0, 0x10000
	s_cselect_b32 s0, 0x12000, s0
	s_lshr_b32 s10, s0, 6
	v_mov_b32_e32 v15, v208
	v_readlane_b32 s4, v254, 19
	s_cmp_ge_i32 s4, s10
	v_readfirstlane_b32 s2, v15
	v_readlane_b32 s5, v254, 20
	s_cbranch_scc1 .LBB0_121
	v_lshlrev_b32_e32 v0, 4, v15
	v_add_u32_e32 v2, 0x2000, v0
	v_ashrrev_i32_e32 v3, 31, v2
	v_lshrrev_b32_e32 v3, 22, v3
	v_add_u32_e32 v3, v2, v3
	v_ashrrev_i32_e32 v3, 10, v3
	v_mul_i32_i24_e32 v4, 0x400, v3
	v_sub_u32_e32 v2, v2, v4
	v_lshrrev_b32_e32 v4, 4, v2
	v_writelane_b32 v255, s69, 54
	s_and_b64 s[6:7], s[34:35], exec
	s_movk_i32 s1, 0xc00
	v_bitop3_b32 v2, v4, v2, 32 bitop3:0x6c
	v_writelane_b32 v255, s76, 56
	s_cselect_b32 s1, s1, 0x1800
	v_ashrrev_i32_e32 v4, 31, v2
	v_writelane_b32 v255, s77, 57
	s_add_u32 s33, s38, s1
	s_mov_b64 s[4:5], s[34:35]
	v_lshrrev_b32_e32 v4, 26, v4
	s_addc_u32 s34, s39, 0
	v_writelane_b32 v255, s4, 50
	v_add_u32_e32 v4, v2, v4
	v_lshlrev_b32_e32 v6, 3, v3
	v_lshlrev_b32_e32 v3, 5, v3
	v_writelane_b32 v255, s5, 51
	s_and_b64 s[6:7], s[4:5], exec
	s_mov_b32 s4, s84
	v_and_b32_e32 v10, 32, v3
	v_and_b32_e32 v3, 0xc0, v4
	v_writelane_b32 v255, s4, 52
	v_sub_u32_e32 v2, v2, v3
	v_ashrrev_i32_e32 v5, 6, v4
	v_writelane_b32 v255, s5, 53
	v_and_b32_e32 v6, -16, v6
	v_ashrrev_i16_sdwa v2, v216, sext(v2) dst_sel:DWORD dst_unused:UNUSED_PAD src0_sel:DWORD src1_sel:BYTE_0
	v_readlane_b32 s5, v255, 49
	v_add_u32_e32 v6, v5, v6
	v_bfe_i32 v11, v2, 0, 16
	v_add_u32_e32 v2, v10, v11
	v_mul_lo_u32 v12, v6, s5
	v_lshlrev_b32_e32 v3, 1, v2
	v_add_lshl_u32 v132, v2, v12, 1
	v_bfe_i32 v2, v15, 27, 1
	v_and_b32_e32 v5, 3, v5
	s_mov_b32 s4, 0x1fffe0
	v_lshrrev_b32_e32 v7, 2, v6
	v_lshlrev_b32_e32 v8, 1, v6
	v_lshrrev_b32_e32 v2, 22, v2
	v_and_or_b32 v5, v6, s4, v5
	v_and_b32_e32 v7, 4, v7
	v_and_b32_e32 v8, 24, v8
	v_add_u32_e32 v2, v0, v2
	v_or3_b32 v5, v5, v7, v8
	v_and_b32_e32 v2, 0xfffffc00, v2
	v_lshl_add_u32 v130, v5, 11, v3
	v_sub_u32_e32 v0, v0, v2
	v_ashrrev_i32_e32 v3, 31, v15
	v_lshrrev_b32_e32 v2, 4, v0
	v_lshrrev_b32_e32 v3, 26, v3
	v_bitop3_b32 v2, v2, v0, 32 bitop3:0x6c
	v_ashrrev_i32_e32 v0, 31, v0
	v_add_u32_e32 v3, v15, v3
	v_lshrrev_b32_e32 v0, 26, v0
	v_ashrrev_i32_e32 v3, 6, v3
	s_cselect_b32 s1, s45, s49
	s_cselect_b32 s11, s44, s48
	s_ashr_i32 s85, s84, 31
	v_add_u32_e32 v0, v2, v0
	v_lshlrev_b32_e32 v4, 3, v3
	s_lshl_b64 s[6:7], s[84:85], 21
	v_ashrrev_i32_e32 v0, 6, v0
	v_and_b32_e32 v4, -16, v4
	s_add_u32 s35, s11, s6
	v_add_u32_e32 v4, v0, v4
	v_and_b32_e32 v5, 3, v0
	s_addc_u32 s72, s1, s7
	s_ashr_i32 s1, s2, 6
	s_waitcnt lgkmcnt(0)
	s_lshl_b32 s78, s5, 8
	s_lshl_b32 s75, s5, 9
	v_and_or_b32 v5, v4, s4, v5
	v_mul_lo_u32 v16, v4, s5
	s_lshr_b32 s77, s0, 9
	v_readlane_b32 s4, v254, 23
	s_lshr_b32 s73, s0, 8
	s_ashr_i32 s6, s2, 8
	s_lshl_b32 s76, s1, 10
	s_or_b32 s84, s77, 1
	v_readlane_b32 s5, v254, 24
	s_and_b64 s[12:13], s[4:5], exec
	s_cselect_b32 s0, s84, s77
	v_readlane_b32 s4, v254, 42
	s_mul_i32 s0, s0, s4
	v_readlane_b32 s4, v254, 43
	s_add_i32 s0, s0, s4
	s_ashr_i32 s7, s0, 31
	s_lshr_b32 s7, s7, 27
	s_add_i32 s7, s0, s7
	v_mul_i32_i24_e32 v0, 64, v0
	s_ashr_i32 s11, s7, 5
	v_sub_u32_e32 v0, v2, v0
	s_lshl_b32 s11, s11, 3
	v_lshlrev_b32_e32 v3, 5, v3
	v_ashrrev_i16_sdwa v0, v216, sext(v0) dst_sel:DWORD dst_unused:UNUSED_PAD src0_sel:DWORD src1_sel:BYTE_0
	s_sub_i32 s12, s73, s11
	v_and_b32_e32 v13, 32, v3
	v_bfe_i32 v14, v0, 0, 16
	s_min_i32 s14, s12, 8
	v_add_u32_e32 v2, v13, v14
	s_sext_i32_i16 s12, s14
	v_lshlrev_b32_e32 v0, 1, v2
	v_add_lshl_u32 v134, v2, v16, 1
	v_cvt_f32_i32_e32 v2, s12
	s_andn2_b32 s7, s7, 31
	s_sub_i32 s7, s0, s7
	v_lshrrev_b32_e32 v6, 2, v4
	v_lshlrev_b32_e32 v7, 1, v4
	v_cvt_f32_i32_e32 v3, s7
	v_rcp_iflag_f32_e32 v4, v2
	s_xor_b32 s0, s7, s12
	s_ashr_i32 s0, s0, 30
	s_or_b32 s0, s0, 1
	v_mul_f32_e32 v4, v3, v4
	v_trunc_f32_e32 v4, v4
	v_fma_f32 v3, -v4, v2, v3
	v_cvt_i32_f32_e32 v4, v4
	v_cmp_ge_f32_e64 s[12:13], |v3|, |v2|
	s_and_b64 s[12:13], s[12:13], exec
	s_cselect_b32 s0, s0, 0
	v_readfirstlane_b32 s12, v4
	s_add_i32 s0, s12, s0
	s_mul_i32 s12, s0, s14
	s_sub_i32 s7, s7, s12
	s_sext_i32_i16 s7, s7
	s_bfe_i64 s[12:13], s[0:1], 0x100000
	s_add_i32 s27, s11, s7
	s_lshl_b64 s[12:13], s[12:13], 19
	v_and_b32_e32 v6, 4, v6
	v_and_b32_e32 v7, 24, v7
	s_add_u32 s70, s35, s12
	v_or3_b32 v5, v5, v6, v7
	s_addc_u32 s71, s72, s13
	s_add_i32 s85, s76, 0
	v_lshl_add_u32 v0, v5, 11, v0
	s_add_i32 m0, s85, 0x10000
	s_mul_i32 s11, s75, s27
	global_load_lds_dwordx4 v0, s[70:71]
	s_add_i32 m0, s85, 0x12000
	s_mul_hi_i32 s7, s75, s27
	s_add_u32 s12, s33, s11
	global_load_lds_dwordx4 v130, s[70:71]
	s_addc_u32 s13, s34, s7
	s_mov_b32 m0, s85
	s_add_i32 s20, s85, 0x2000
	global_load_lds_dwordx4 v134, s[12:13]
	s_mov_b32 m0, s20
	s_add_u32 s14, s70, 0x40000
	global_load_lds_dwordx4 v132, s[12:13]
	s_addc_u32 s15, s71, 0
	s_add_i32 m0, s85, 0x14000
	s_load_dword s23, s[86:87], 0x0
	global_load_lds_dwordx4 v0, s[14:15]
	s_add_i32 m0, s85, 0x16000
	v_mov_b32_e32 v131, v1
	global_load_lds_dwordx4 v130, s[14:15]
	s_add_u32 s14, s12, s78
	s_addc_u32 s15, s13, 0
	s_add_i32 s21, s85, 0x4000
	s_mov_b32 m0, s21
	s_add_i32 s22, s85, 0x6000
	global_load_lds_dwordx4 v134, s[14:15]
	s_mov_b32 m0, s22
	v_mov_b32_e32 v135, v1
	global_load_lds_dwordx4 v132, s[14:15]
	v_mov_b32_e32 v133, v1
	v_lshl_add_u64 v[8:9], s[70:71], 0, v[0:1]
	v_lshl_add_u64 v[6:7], s[70:71], 0, v[130:131]
	v_lshl_add_u64 v[4:5], s[12:13], 0, v[134:135]
	s_cmp_lg_u32 s6, 1
	v_lshl_add_u64 v[2:3], s[12:13], 0, v[132:133]
	s_cbranch_scc1 .LBB0_110
	s_setprio 1
	s_barrier

; DI int opaque_tid() { int t = threadIdx.x; asm volatile("" : "+v"(t)); return t; }
; #define PG8_BAR __builtin_amdgcn_s_barrier()
; template <class Epi>
; DI void gemm_phase(PG8_LAS unsigned char* lds, const Gemm g, const StaticOrder& S, const Epi& E) {
;   const int tid = opaque_tid(), wid = __builtin_amdgcn_readfirstlane(tid >> 6), lane = tid & 63, wr = wid >> 2, wc = wid & 3, fr = lane & 15, fq = lane >> 4;
;   const int K = g.K, nt = K / BK, lda = g.lda;
;   unsigned voffA[2], voffB[2];
; #pragma unroll
;   for (int i = 0; i < 2; ++i) { int R, C; stage_rc(tid * 16 + i * 8192, R, C); const int Rb = Epi::PERM ? ((R & ~31) + perm32(R & 31)) : R;
;     voffA[i] = (unsigned)(R * lda + C) * 2u; voffB[i] = (unsigned)(Rb * K + C) * 2u; }
;   const size_t kstep = (size_t)(BK * 2);
;   const size_t hstepA = (size_t)HALF * lda * 2, hstepB = (size_t)HALF * K * 2;
;   const size_t tstepA = 2 * hstepA, tstepB = 2 * hstepB;
;   const unsigned ldsw = (unsigned)wid * 1024u;
;   const int aoff = lds_byte(wr * 64 + fr, fq * 8), boff = lds_byte(wc * 32 + fr, fq * 8);
;     ...
;   Unit cur, nxt; int ui = 0;
;   if (!S.next(0, cur)) return;
;   f32x4 acc[2][2][4][2];
; #pragma unroll
;   for (int a = 0; a < 2; ++a)
; #pragma unroll
;     for (int b = 0; b < 2; ++b)
; #pragma unroll
;       for (int m = 0; m < 4; ++m)
; #pragma unroll
;         for (int n = 0; n < 2; ++n) acc[a][b][m][n] = (f32x4){0.f, 0.f, 0.f, 0.f};
;   bf16x8 At[4][2], B0[2][2], B1[2][2];
;   const char* cA = (const char*)g.A + (size_t)cur.pm * tstepA; const char* cB = (const char*)g.Bt + (size_t)cur.pn * tstepB;
;   PG8_STAGE(PG8_SB(0, 0), cB, voffB); PG8_STAGE(PG8_SA(0, 0), cA, voffA); PG8_STAGE(PG8_SB(0, 1), cB + hstepB, voffB); PG8_STAGE(PG8_SA(0, 1), cA + hstepA, voffA);
;   if (wr == 1) PG8_BAR;
; __global__ void __launch_bounds__(512, 2) mega(Params p, int ph_lo, int ph_hi) {
;     ...
;         else if (layer < 3) gemm_phase<EPI_B>(p, p.u, 1024, p.wt_b_in + (size_t)jl * 4096 * 1024, TT, 4096, smem);
;         else {
;           gemm_phase<EPI_B>(p, p.u, 1024, p.wt_b_in + (size_t)jl * 4096 * 1024, TL, 4096, smem);
;           gemm_phase<EPI_B>(p, p.u + (size_t)TL * 1024, 1024, p.wt_b_in + (size_t)jl * 4096 * 1024 + (size_t)1024 * 1024, TC, 2048, smem, 256, 4);
.LBB0_205:
	s_cmp_eq_u32 s69, 1
	s_mov_b64 s[0:1], -1
	s_cbranch_scc1 .LBB0_733
	v_readlane_b32 s4, v255, 47
	v_readlane_b32 s5, v255, 48
	s_and_b64 vcc, exec, s[4:5]
	s_cbranch_vccz .LBB0_577
	s_ashr_i32 s85, s84, 31
	s_waitcnt lgkmcnt(0)
	s_load_dword s78, s[86:87], 0x0
	s_lshl_b64 s[0:1], s[84:85], 23
	s_add_u32 s69, s46, s0
	s_addc_u32 s93, s47, s1
	v_readlane_b32 s0, v255, 46
	s_cmp_gt_i32 s0, 2
	s_mov_b64 s[0:1], -1
	s_cbranch_scc0 .LBB0_470
	v_readlane_b32 s0, v254, 13
	v_mov_b32_e32 v8, v208
	v_readlane_b32 s1, v254, 14
	v_writelane_b32 v255, s34, 50
	s_andn2_b64 vcc, exec, s[0:1]
	v_readfirstlane_b32 s2, v8
	v_writelane_b32 v255, s35, 51
	s_cbranch_vccnz .LBB0_339
	v_lshlrev_b32_e32 v0, 4, v8
	v_add_u32_e32 v3, 0x2000, v0
	v_ashrrev_i32_e32 v2, 31, v3
	v_lshrrev_b32_e32 v2, 22, v2
	v_add_u32_e32 v2, v3, v2
	v_ashrrev_i32_e32 v2, 10, v2
	v_mul_i32_i24_e32 v4, 0x400, v2
	v_sub_u32_e32 v3, v3, v4
	v_lshrrev_b32_e32 v4, 4, v3
	v_bitop3_b32 v4, v4, v3, 32 bitop3:0x6c
	v_ashrrev_i32_e32 v3, 31, v4
	v_lshrrev_b32_e32 v3, 26, v3
	v_add_u32_e32 v5, v4, v3
	v_lshlrev_b32_e32 v6, 3, v2
	v_ashrrev_i32_e32 v3, 6, v5
	v_and_b32_e32 v6, -16, v6
	v_add_u32_e32 v6, v3, v6
	v_and_b32_e32 v7, 3, v3
	s_mov_b32 s6, 0x1fffe0
	v_lshrrev_b32_e32 v9, 2, v6
	v_lshlrev_b32_e32 v10, 1, v6
	v_and_b32_e32 v5, 0xc0, v5
	v_and_or_b32 v7, v6, s6, v7
	v_and_b32_e32 v9, 4, v9
	v_and_b32_e32 v10, 24, v10
	v_sub_u32_e32 v4, v4, v5
	v_or3_b32 v7, v7, v9, v10
	v_lshlrev_b32_e32 v9, 5, v2
	v_ashrrev_i16_sdwa v4, v216, sext(v4) dst_sel:DWORD dst_unused:UNUSED_PAD src0_sel:DWORD src1_sel:BYTE_0
	v_and_b32_e32 v9, 32, v9
	v_bfe_i32 v4, v4, 0, 16
	v_add_lshl_u32 v5, v9, v4, 1
	v_lshl_add_u32 v138, v7, 11, v5
	v_lshl_add_u32 v140, v6, 11, v5
	v_bfe_i32 v5, v8, 27, 1
	v_lshrrev_b32_e32 v5, 22, v5
	v_add_u32_e32 v5, v0, v5
	v_and_b32_e32 v5, 0xfffffc00, v5
	v_sub_u32_e32 v0, v0, v5
	v_lshrrev_b32_e32 v5, 4, v0
	v_bitop3_b32 v7, v5, v0, 32 bitop3:0x6c
	v_ashrrev_i32_e32 v0, 31, v0
	v_lshrrev_b32_e32 v0, 26, v0
	v_add_u32_e32 v0, v7, v0
	v_ashrrev_i32_e32 v5, 6, v0
	v_ashrrev_i32_e32 v0, 31, v8
	v_lshrrev_b32_e32 v0, 26, v0
	v_add_u32_e32 v0, v8, v0
	v_ashrrev_i32_e32 v6, 6, v0
	v_lshlrev_b32_e32 v0, 3, v6
	v_and_b32_e32 v0, -16, v0
	v_add_u32_e32 v9, v5, v0
	v_and_b32_e32 v0, 3, v5
	v_lshrrev_b32_e32 v10, 2, v9
	v_lshlrev_b32_e32 v11, 1, v9
	v_and_or_b32 v0, v9, s6, v0
	v_and_b32_e32 v10, 4, v10
	v_and_b32_e32 v11, 24, v11
	v_or3_b32 v0, v0, v10, v11
	v_mul_i32_i24_e32 v11, 64, v5
	s_ashr_i32 s0, s2, 6
	v_sub_u32_e32 v7, v7, v11
	s_ashr_i32 s1, s2, 8
	s_lshl_b32 s34, s0, 10
	v_lshlrev_b32_e32 v10, 5, v6
	v_ashrrev_i16_sdwa v7, v216, sext(v7) dst_sel:DWORD dst_unused:UNUSED_PAD src0_sel:DWORD src1_sel:BYTE_0
	v_readlane_b32 s6, v254, 55
	v_and_b32_e32 v10, 32, v10
	v_bfe_i32 v7, v7, 0, 16
	v_readlane_b32 s7, v254, 56
	s_add_u32 s10, s69, s6
	v_add_lshl_u32 v10, v10, v7, 1
	s_addc_u32 s11, s93, s7
	s_add_i32 s35, s34, 0
	v_lshl_add_u32 v0, v0, 11, v10
	s_add_i32 m0, s35, 0x10000
	v_readlane_b32 s6, v254, 59
	global_load_lds_dwordx4 v0, s[10:11]
	s_add_i32 m0, s35, 0x12000
	v_lshl_add_u32 v148, v9, 11, v10
	global_load_lds_dwordx4 v138, s[10:11]
	s_mov_b32 m0, s35
	v_readlane_b32 s7, v254, 60
	s_add_i32 s75, s35, 0x2000
	s_mov_b32 s72, s84
	s_nop 2
	global_load_lds_dwordx4 v148, s[6:7]
	s_mov_b32 m0, s75
	s_nop 0
	global_load_lds_dwordx4 v140, s[6:7]
	s_add_u32 s6, s10, 0x40000
	s_addc_u32 s7, s11, 0
	s_add_i32 m0, s35, 0x14000
	s_add_i32 s84, s35, 0x4000
	global_load_lds_dwordx4 v0, s[6:7]
	s_add_i32 m0, s35, 0x16000
	s_add_i32 s85, s35, 0x6000
	global_load_lds_dwordx4 v138, s[6:7]
	v_readlane_b32 s6, v254, 61
	s_mov_b32 m0, s84
	v_readlane_b32 s7, v254, 62
	s_cmp_lg_u32 s1, 1
	s_nop 3
	global_load_lds_dwordx4 v148, s[6:7]
	s_mov_b32 m0, s85
	s_nop 0
	global_load_lds_dwordx4 v140, s[6:7]
	s_cbranch_scc1 .LBB0_211
	s_setprio 1
	s_barrier

; DI int opaque_tid() { int t = threadIdx.x; asm volatile("" : "+v"(t)); return t; }
; #define PG8_STAGE(bufoff, gbase, voff) do { _Pragma("unroll") for (int _i = 0; _i < 2; ++_i) \
;     __builtin_amdgcn_global_load_lds((const unsigned*)((const char*)(gbase) + (voff)[_i]), (PG8_LAS unsigned*)(lds + (bufoff) + ldsw + _i * 8192), 16, 0, 0); } while (0)
; #define PG8_BAR __builtin_amdgcn_s_barrier()
; template <class Epi>
; DI void gemm_phase(PG8_LAS unsigned char* lds, const Gemm g, const StaticOrder& S, const Epi& E) {
;   const int tid = opaque_tid(), wid = __builtin_amdgcn_readfirstlane(tid >> 6), lane = tid & 63, wr = wid >> 2, wc = wid & 3, fr = lane & 15, fq = lane >> 4;
;   const int K = g.K, nt = K / BK, lda = g.lda;
;   unsigned voffA[2], voffB[2];
; #pragma unroll
;   for (int i = 0; i < 2; ++i) { int R, C; stage_rc(tid * 16 + i * 8192, R, C); const int Rb = Epi::PERM ? ((R & ~31) + perm32(R & 31)) : R;
;     voffA[i] = (unsigned)(R * lda + C) * 2u; voffB[i] = (unsigned)(Rb * K + C) * 2u; }
;   const size_t kstep = (size_t)(BK * 2);
;   const size_t hstepA = (size_t)HALF * lda * 2, hstepB = (size_t)HALF * K * 2;
;   const size_t tstepA = 2 * hstepA, tstepB = 2 * hstepB;
;   const unsigned ldsw = (unsigned)wid * 1024u;
;   const int aoff = lds_byte(wr * 64 + fr, fq * 8), boff = lds_byte(wc * 32 + fr, fq * 8);
;     ...
;   Unit cur, nxt; int ui = 0;
;   if (!S.next(0, cur)) return;
;   f32x4 acc[2][2][4][2];
; #pragma unroll
;   for (int a = 0; a < 2; ++a)
; #pragma unroll
;     for (int b = 0; b < 2; ++b)
; #pragma unroll
;       for (int m = 0; m < 4; ++m)
; #pragma unroll
;         for (int n = 0; n < 2; ++n) acc[a][b][m][n] = (f32x4){0.f, 0.f, 0.f, 0.f};
;   bf16x8 At[4][2], B0[2][2], B1[2][2];
;   const char* cA = (const char*)g.A + (size_t)cur.pm * tstepA; const char* cB = (const char*)g.Bt + (size_t)cur.pn * tstepB;
;   PG8_STAGE(PG8_SB(0, 0), cB, voffB); PG8_STAGE(PG8_SA(0, 0), cA, voffA); PG8_STAGE(PG8_SB(0, 1), cB + hstepB, voffB); PG8_STAGE(PG8_SA(0, 1), cA + hstepA, voffA);
;   if (wr == 1) PG8_BAR;
;     ...
;   __syncthreads();
; __global__ void __launch_bounds__(512, 2) mega(Params p, int ph_lo, int ph_hi) {
;     ...
;           gemm_phase<EPI_B>(p, p.u + (size_t)TL * 1024, 1024, p.wt_b_in + (size_t)jl * 4096 * 1024 + (size_t)1024 * 1024, TC, 2048, smem, 256, 4);
.LBB0_339:
	v_readlane_b32 s0, v254, 15
	v_mov_b32_e32 v8, v208
	v_readlane_b32 s1, v254, 16
	s_waitcnt vmcnt(0) lgkmcnt(0)
	s_barrier
	s_andn2_b64 vcc, exec, s[0:1]
	v_readfirstlane_b32 s73, v8
	s_cbranch_vccnz .LBB0_469
	v_lshlrev_b32_e32 v0, 4, v8
	v_add_u32_e32 v3, 0x2000, v0
	v_ashrrev_i32_e32 v2, 31, v3
	v_lshrrev_b32_e32 v2, 22, v2
	v_add_u32_e32 v2, v3, v2
	v_ashrrev_i32_e32 v2, 10, v2
	v_mul_i32_i24_e32 v4, 0x400, v2
	v_sub_u32_e32 v3, v3, v4
	v_lshrrev_b32_e32 v4, 4, v3
	v_bitop3_b32 v4, v4, v3, 32 bitop3:0x6c
	v_ashrrev_i32_e32 v3, 31, v4
	v_lshrrev_b32_e32 v3, 26, v3
	v_add_u32_e32 v5, v4, v3
	v_lshlrev_b32_e32 v6, 3, v2
	v_ashrrev_i32_e32 v3, 6, v5
	v_and_b32_e32 v6, -16, v6
	v_add_u32_e32 v6, v3, v6
	v_and_b32_e32 v7, 3, v3
	s_mov_b32 s2, 0x1fffe0
	v_lshrrev_b32_e32 v9, 2, v6
	v_lshlrev_b32_e32 v10, 1, v6
	v_and_b32_e32 v5, 0xc0, v5
	v_and_or_b32 v7, v6, s2, v7
	v_and_b32_e32 v9, 4, v9
	v_and_b32_e32 v10, 24, v10
	v_sub_u32_e32 v4, v4, v5
	v_or3_b32 v7, v7, v9, v10
	v_lshlrev_b32_e32 v9, 5, v2
	v_ashrrev_i16_sdwa v4, v216, sext(v4) dst_sel:DWORD dst_unused:UNUSED_PAD src0_sel:DWORD src1_sel:BYTE_0
	v_and_b32_e32 v9, 32, v9
	v_bfe_i32 v4, v4, 0, 16
	v_add_lshl_u32 v5, v9, v4, 1
	v_lshl_add_u32 v138, v7, 11, v5
	v_lshl_add_u32 v140, v6, 11, v5
	v_bfe_i32 v5, v8, 27, 1
	v_lshrrev_b32_e32 v5, 22, v5
	v_add_u32_e32 v5, v0, v5
	v_and_b32_e32 v5, 0xfffffc00, v5
	v_sub_u32_e32 v0, v0, v5
	v_lshrrev_b32_e32 v5, 4, v0
	v_bitop3_b32 v7, v5, v0, 32 bitop3:0x6c
	v_ashrrev_i32_e32 v0, 31, v0
	v_lshrrev_b32_e32 v0, 26, v0
	v_add_u32_e32 v0, v7, v0
	v_ashrrev_i32_e32 v5, 6, v0
	v_ashrrev_i32_e32 v0, 31, v8
	v_lshrrev_b32_e32 v0, 26, v0
	v_add_u32_e32 v0, v8, v0
	v_ashrrev_i32_e32 v6, 6, v0
	v_lshlrev_b32_e32 v0, 3, v6
	v_and_b32_e32 v0, -16, v0
	v_add_u32_e32 v9, v5, v0
	v_and_b32_e32 v0, 3, v5
	v_lshrrev_b32_e32 v10, 2, v9
	v_lshlrev_b32_e32 v11, 1, v9
	v_and_or_b32 v0, v9, s2, v0
	v_and_b32_e32 v10, 4, v10
	v_and_b32_e32 v11, 24, v11
	s_add_u32 s34, s69, 0x200000
	v_or3_b32 v0, v0, v10, v11
	v_mul_i32_i24_e32 v11, 64, v5
	s_addc_u32 s35, s93, 0
	s_ashr_i32 s0, s73, 6
	v_sub_u32_e32 v7, v7, v11
	s_ashr_i32 s1, s73, 8
	s_lshl_b32 s75, s0, 10
	v_lshlrev_b32_e32 v10, 5, v6
	v_ashrrev_i16_sdwa v7, v216, sext(v7) dst_sel:DWORD dst_unused:UNUSED_PAD src0_sel:DWORD src1_sel:BYTE_0
	v_readlane_b32 s6, v254, 63
	v_and_b32_e32 v10, 32, v10
	v_bfe_i32 v7, v7, 0, 16
	v_readlane_b32 s7, v255, 0
	s_add_u32 s10, s34, s6
	s_mov_b32 s72, s84
	v_add_lshl_u32 v10, v10, v7, 1
	s_addc_u32 s11, s35, s7
	s_add_i32 s84, s75, 0
	v_lshl_add_u32 v0, v0, 11, v10
	s_add_i32 m0, s84, 0x10000
	v_readlane_b32 s6, v255, 5
	global_load_lds_dwordx4 v0, s[10:11]
	s_add_i32 m0, s84, 0x12000
	v_lshl_add_u32 v148, v9, 11, v10
	global_load_lds_dwordx4 v138, s[10:11]
	s_mov_b32 m0, s84
	v_readlane_b32 s7, v255, 6
	s_add_i32 s85, s84, 0x2000
	s_nop 3
	global_load_lds_dwordx4 v148, s[6:7]
	s_mov_b32 m0, s85
	s_nop 0
	global_load_lds_dwordx4 v140, s[6:7]
	s_add_u32 s6, s10, 0x40000
	s_addc_u32 s7, s11, 0
	s_add_i32 m0, s84, 0x14000
	s_add_i32 s86, s84, 0x4000
	global_load_lds_dwordx4 v0, s[6:7]
	s_add_i32 m0, s84, 0x16000
	s_add_i32 s87, s84, 0x6000
	global_load_lds_dwordx4 v138, s[6:7]
	v_readlane_b32 s6, v255, 7
	s_mov_b32 m0, s86
	v_readlane_b32 s7, v255, 8
	s_cmp_lg_u32 s1, 1
	s_nop 3
	global_load_lds_dwordx4 v148, s[6:7]
	s_mov_b32 m0, s87
	s_nop 0
	global_load_lds_dwordx4 v140, s[6:7]
	s_cbranch_scc1 .LBB0_342
	s_setprio 1
	s_barrier

; DI int opaque_tid() { int t = threadIdx.x; asm volatile("" : "+v"(t)); return t; }
; #define PG8_STAGE(bufoff, gbase, voff) do { _Pragma("unroll") for (int _i = 0; _i < 2; ++_i) \
;     __builtin_amdgcn_global_load_lds((const unsigned*)((const char*)(gbase) + (voff)[_i]), (PG8_LAS unsigned*)(lds + (bufoff) + ldsw + _i * 8192), 16, 0, 0); } while (0)
; #define PG8_BAR __builtin_amdgcn_s_barrier()
; template <class Epi>
; DI void gemm_phase(PG8_LAS unsigned char* lds, const Gemm g, const StaticOrder& S, const Epi& E) {
;   const int tid = opaque_tid(), wid = __builtin_amdgcn_readfirstlane(tid >> 6), lane = tid & 63, wr = wid >> 2, wc = wid & 3, fr = lane & 15, fq = lane >> 4;
;   const int K = g.K, nt = K / BK, lda = g.lda;
;   unsigned voffA[2], voffB[2];
; #pragma unroll
;   for (int i = 0; i < 2; ++i) { int R, C; stage_rc(tid * 16 + i * 8192, R, C); const int Rb = Epi::PERM ? ((R & ~31) + perm32(R & 31)) : R;
;     voffA[i] = (unsigned)(R * lda + C) * 2u; voffB[i] = (unsigned)(Rb * K + C) * 2u; }
;   const size_t kstep = (size_t)(BK * 2);
;   const size_t hstepA = (size_t)HALF * lda * 2, hstepB = (size_t)HALF * K * 2;
;   const size_t tstepA = 2 * hstepA, tstepB = 2 * hstepB;
;   const unsigned ldsw = (unsigned)wid * 1024u;
;   const int aoff = lds_byte(wr * 64 + fr, fq * 8), boff = lds_byte(wc * 32 + fr, fq * 8);
;     ...
;   Unit cur, nxt; int ui = 0;
;   if (!S.next(0, cur)) return;
;   f32x4 acc[2][2][4][2];
; #pragma unroll
;   for (int a = 0; a < 2; ++a)
; #pragma unroll
;     for (int b = 0; b < 2; ++b)
; #pragma unroll
;       for (int m = 0; m < 4; ++m)
; #pragma unroll
;         for (int n = 0; n < 2; ++n) acc[a][b][m][n] = (f32x4){0.f, 0.f, 0.f, 0.f};
;   bf16x8 At[4][2], B0[2][2], B1[2][2];
;   const char* cA = (const char*)g.A + (size_t)cur.pm * tstepA; const char* cB = (const char*)g.Bt + (size_t)cur.pn * tstepB;
;   PG8_STAGE(PG8_SB(0, 0), cB, voffB); PG8_STAGE(PG8_SA(0, 0), cA, voffA); PG8_STAGE(PG8_SB(0, 1), cB + hstepB, voffB); PG8_STAGE(PG8_SA(0, 1), cA + hstepA, voffA);
;   if (wr == 1) PG8_BAR;
; __global__ void __launch_bounds__(512, 2) mega(Params p, int ph_lo, int ph_hi) {
;     ...
;         else if (layer < 3) gemm_phase<EPI_B>(p, p.u, 1024, p.wt_b_in + (size_t)jl * 4096 * 1024, TT, 4096, smem);
.LBB0_470:
	s_and_b64 vcc, exec, s[0:1]
	s_cbranch_vccz .LBB0_576
	v_readlane_b32 s0, v254, 17
	v_mov_b32_e32 v8, v208
	v_readlane_b32 s1, v254, 18
	s_andn2_b64 vcc, exec, s[0:1]
	v_readfirstlane_b32 s2, v8
	s_cbranch_vccnz .LBB0_758
	v_lshlrev_b32_e32 v0, 4, v8
	v_add_u32_e32 v3, 0x2000, v0
	v_ashrrev_i32_e32 v2, 31, v3
	v_lshrrev_b32_e32 v2, 22, v2
	v_add_u32_e32 v2, v3, v2
	v_ashrrev_i32_e32 v2, 10, v2
	v_mul_i32_i24_e32 v4, 0x400, v2
	v_sub_u32_e32 v3, v3, v4
	v_lshrrev_b32_e32 v4, 4, v3
	v_bitop3_b32 v4, v4, v3, 32 bitop3:0x6c
	v_ashrrev_i32_e32 v3, 31, v4
	v_lshrrev_b32_e32 v3, 26, v3
	v_add_u32_e32 v5, v4, v3
	v_lshlrev_b32_e32 v6, 3, v2
	v_ashrrev_i32_e32 v3, 6, v5
	v_and_b32_e32 v6, -16, v6
	v_add_u32_e32 v6, v3, v6
	v_and_b32_e32 v7, 3, v3
	s_mov_b32 s6, 0x1fffe0
	v_lshrrev_b32_e32 v9, 2, v6
	v_lshlrev_b32_e32 v10, 1, v6
	v_and_b32_e32 v5, 0xc0, v5
	v_and_or_b32 v7, v6, s6, v7
	v_and_b32_e32 v9, 4, v9
	v_and_b32_e32 v10, 24, v10
	v_sub_u32_e32 v4, v4, v5
	v_or3_b32 v7, v7, v9, v10
	v_lshlrev_b32_e32 v9, 5, v2
	v_ashrrev_i16_sdwa v4, v216, sext(v4) dst_sel:DWORD dst_unused:UNUSED_PAD src0_sel:DWORD src1_sel:BYTE_0
	v_and_b32_e32 v9, 32, v9
	v_bfe_i32 v4, v4, 0, 16
	v_add_lshl_u32 v5, v9, v4, 1
	v_lshl_add_u32 v138, v7, 11, v5
	v_lshl_add_u32 v140, v6, 11, v5
	v_bfe_i32 v5, v8, 27, 1
	v_lshrrev_b32_e32 v5, 22, v5
	v_add_u32_e32 v5, v0, v5
	v_and_b32_e32 v5, 0xfffffc00, v5
	v_sub_u32_e32 v0, v0, v5
	v_lshrrev_b32_e32 v5, 4, v0
	v_bitop3_b32 v7, v5, v0, 32 bitop3:0x6c
	v_ashrrev_i32_e32 v0, 31, v0
	v_lshrrev_b32_e32 v0, 26, v0
	v_add_u32_e32 v0, v7, v0
	v_ashrrev_i32_e32 v5, 6, v0
	v_ashrrev_i32_e32 v0, 31, v8
	v_lshrrev_b32_e32 v0, 26, v0
	v_add_u32_e32 v0, v8, v0
	v_ashrrev_i32_e32 v6, 6, v0
	v_lshlrev_b32_e32 v0, 3, v6
	v_and_b32_e32 v0, -16, v0
	v_add_u32_e32 v9, v5, v0
	v_and_b32_e32 v0, 3, v5
	v_lshrrev_b32_e32 v10, 2, v9
	v_lshlrev_b32_e32 v11, 1, v9
	v_and_or_b32 v0, v9, s6, v0
	v_and_b32_e32 v10, 4, v10
	v_and_b32_e32 v11, 24, v11
	v_writelane_b32 v255, s34, 50
	v_or3_b32 v0, v0, v10, v11
	v_mul_i32_i24_e32 v11, 64, v5
	v_writelane_b32 v255, s35, 51
	s_ashr_i32 s0, s2, 6
	v_sub_u32_e32 v7, v7, v11
	s_ashr_i32 s1, s2, 8
	s_lshl_b32 s34, s0, 10
	v_lshlrev_b32_e32 v10, 5, v6
	v_ashrrev_i16_sdwa v7, v216, sext(v7) dst_sel:DWORD dst_unused:UNUSED_PAD src0_sel:DWORD src1_sel:BYTE_0
	v_readlane_b32 s6, v255, 9
	v_and_b32_e32 v10, 32, v10
	v_bfe_i32 v7, v7, 0, 16
	v_readlane_b32 s7, v255, 10
	s_add_u32 s10, s69, s6
	v_add_lshl_u32 v10, v10, v7, 1
	s_addc_u32 s11, s93, s7
	s_add_i32 s35, s34, 0
	v_lshl_add_u32 v0, v0, 11, v10
	s_add_i32 m0, s35, 0x10000
	v_readlane_b32 s6, v255, 13
	global_load_lds_dwordx4 v0, s[10:11]
	s_add_i32 m0, s35, 0x12000
	v_lshl_add_u32 v148, v9, 11, v10
	global_load_lds_dwordx4 v138, s[10:11]
	s_mov_b32 m0, s35
	v_readlane_b32 s7, v255, 14
	s_add_i32 s75, s35, 0x2000
	s_mov_b32 s72, s84
	s_nop 2
	global_load_lds_dwordx4 v148, s[6:7]
	s_mov_b32 m0, s75
	s_nop 0
	global_load_lds_dwordx4 v140, s[6:7]
	s_add_u32 s6, s10, 0x40000
	s_addc_u32 s7, s11, 0
	s_add_i32 m0, s35, 0x14000
	s_add_i32 s84, s35, 0x4000
	global_load_lds_dwordx4 v0, s[6:7]
	s_add_i32 m0, s35, 0x16000
	s_add_i32 s85, s35, 0x6000
	global_load_lds_dwordx4 v138, s[6:7]
	v_readlane_b32 s6, v255, 15
	s_mov_b32 m0, s84
	v_readlane_b32 s7, v255, 16
	s_cmp_lg_u32 s1, 1
	s_nop 3
	global_load_lds_dwordx4 v148, s[6:7]
	s_mov_b32 m0, s85
	s_nop 0
	global_load_lds_dwordx4 v140, s[6:7]
	s_cbranch_scc1 .LBB0_474
	s_setprio 1
	s_barrier

; DI int opaque_tid() { int t = threadIdx.x; asm volatile("" : "+v"(t)); return t; }
; #define PG8_STAGE(bufoff, gbase, voff) do { _Pragma("unroll") for (int _i = 0; _i < 2; ++_i) \
;     __builtin_amdgcn_global_load_lds((const unsigned*)((const char*)(gbase) + (voff)[_i]), (PG8_LAS unsigned*)(lds + (bufoff) + ldsw + _i * 8192), 16, 0, 0); } while (0)
; #define PG8_BAR __builtin_amdgcn_s_barrier()
; template <class Epi>
; DI void gemm_phase(PG8_LAS unsigned char* lds, const Gemm g, const StaticOrder& S, const Epi& E) {
;   const int tid = opaque_tid(), wid = __builtin_amdgcn_readfirstlane(tid >> 6), lane = tid & 63, wr = wid >> 2, wc = wid & 3, fr = lane & 15, fq = lane >> 4;
;   const int K = g.K, nt = K / BK, lda = g.lda;
;   unsigned voffA[2], voffB[2];
; #pragma unroll
;   for (int i = 0; i < 2; ++i) { int R, C; stage_rc(tid * 16 + i * 8192, R, C); const int Rb = Epi::PERM ? ((R & ~31) + perm32(R & 31)) : R;
;     voffA[i] = (unsigned)(R * lda + C) * 2u; voffB[i] = (unsigned)(Rb * K + C) * 2u; }
;   const size_t kstep = (size_t)(BK * 2);
;   const size_t hstepA = (size_t)HALF * lda * 2, hstepB = (size_t)HALF * K * 2;
;   const size_t tstepA = 2 * hstepA, tstepB = 2 * hstepB;
;   const unsigned ldsw = (unsigned)wid * 1024u;
;   const int aoff = lds_byte(wr * 64 + fr, fq * 8), boff = lds_byte(wc * 32 + fr, fq * 8);
;     ...
;   Unit cur, nxt; int ui = 0;
;   if (!S.next(0, cur)) return;
;   f32x4 acc[2][2][4][2];
; #pragma unroll
;   for (int a = 0; a < 2; ++a)
; #pragma unroll
;     for (int b = 0; b < 2; ++b)
; #pragma unroll
;       for (int m = 0; m < 4; ++m)
; #pragma unroll
;         for (int n = 0; n < 2; ++n) acc[a][b][m][n] = (f32x4){0.f, 0.f, 0.f, 0.f};
;   bf16x8 At[4][2], B0[2][2], B1[2][2];
;   const char* cA = (const char*)g.A + (size_t)cur.pm * tstepA; const char* cB = (const char*)g.Bt + (size_t)cur.pn * tstepB;
;   PG8_STAGE(PG8_SB(0, 0), cB, voffB); PG8_STAGE(PG8_SA(0, 0), cA, voffA); PG8_STAGE(PG8_SB(0, 1), cB + hstepB, voffB); PG8_STAGE(PG8_SA(0, 1), cA + hstepA, voffA);
;   if (wr == 1) PG8_BAR;
; __global__ void __launch_bounds__(512, 2) mega(Params p, int ph_lo, int ph_hi) {
;     ...
;         if (isA) gemm_phase<EPI_A>(p, p.u, 1024, p.wt_a_in + (size_t)jl * 2560 * 1024, TT, 2560, smem);
.LBB0_591:
	s_or_b64 exec, exec, s[0:1]
	v_readlane_b32 s0, v254, 21
	v_mov_b32_e32 v7, v208
	v_readlane_b32 s1, v254, 22
	s_waitcnt lgkmcnt(0)
	s_barrier
	s_andn2_b64 vcc, exec, s[0:1]
	v_readfirstlane_b32 s93, v7
	s_cbranch_vccnz .LBB0_731
	v_lshlrev_b32_e32 v0, 4, v7
	v_add_u32_e32 v2, 0x2000, v0
	v_ashrrev_i32_e32 v3, 31, v2
	v_lshrrev_b32_e32 v3, 22, v3
	v_add_u32_e32 v3, v2, v3
	v_ashrrev_i32_e32 v6, 10, v3
	v_mul_i32_i24_e32 v3, 0x400, v6
	v_sub_u32_e32 v2, v2, v3
	v_lshrrev_b32_e32 v3, 4, v2
	v_bitop3_b32 v2, v3, v2, 32 bitop3:0x6c
	v_ashrrev_i32_e32 v3, 31, v2
	v_lshrrev_b32_e32 v3, 26, v3
	s_ashr_i32 s1, s93, 6
	v_add_u32_e32 v3, v2, v3
	v_lshlrev_b32_e32 v4, 3, v6
	s_ashr_i32 s0, s93, 8
	s_lshl_b32 s75, s1, 10
	s_mul_i32 s6, s84, 0x500000
	v_ashrrev_i32_e32 v8, 6, v3
	v_and_b32_e32 v4, -16, v4
	s_mul_hi_i32 s2, s84, 0x500000
	s_add_u32 s90, s42, s6
	v_add_u32_e32 v4, v8, v4
	s_addc_u32 s4, s43, s2
	v_and_b32_e32 v5, 3, v8
	s_mov_b32 s2, 0x1fffe0
	v_lshrrev_b32_e32 v9, 2, v4
	v_lshlrev_b32_e32 v10, 1, v4
	v_and_b32_e32 v3, 0xc0, v3
	v_and_or_b32 v5, v4, s2, v5
	v_and_b32_e32 v9, 4, v9
	v_and_b32_e32 v10, 24, v10
	v_sub_u32_e32 v2, v2, v3
	v_or3_b32 v5, v5, v9, v10
	v_lshlrev_b32_e32 v9, 5, v6
	v_ashrrev_i16_sdwa v2, v216, sext(v2) dst_sel:DWORD dst_unused:UNUSED_PAD src0_sel:DWORD src1_sel:BYTE_0
	v_and_b32_e32 v10, 32, v9
	v_bfe_i32 v9, v2, 0, 16
	v_add_lshl_u32 v2, v10, v9, 1
	v_lshl_add_u32 v138, v5, 11, v2
	v_lshl_add_u32 v140, v4, 11, v2
	v_bfe_i32 v2, v7, 27, 1
	v_lshrrev_b32_e32 v2, 22, v2
	v_add_u32_e32 v2, v0, v2
	v_and_b32_e32 v2, 0xfffffc00, v2
	v_sub_u32_e32 v0, v0, v2
	v_lshrrev_b32_e32 v2, 4, v0
	v_bitop3_b32 v2, v2, v0, 32 bitop3:0x6c
	v_ashrrev_i32_e32 v0, 31, v0
	v_lshrrev_b32_e32 v0, 26, v0
	v_add_u32_e32 v0, v2, v0
	v_ashrrev_i32_e32 v10, 6, v0
	v_ashrrev_i32_e32 v0, 31, v7
	v_lshrrev_b32_e32 v0, 26, v0
	v_add_u32_e32 v0, v7, v0
	v_ashrrev_i32_e32 v11, 6, v0
	v_lshlrev_b32_e32 v0, 3, v11
	v_and_b32_e32 v0, -16, v0
	v_add_u32_e32 v3, v10, v0
	v_and_b32_e32 v0, 3, v10
	v_lshrrev_b32_e32 v4, 2, v3
	v_lshlrev_b32_e32 v5, 1, v3
	v_and_or_b32 v0, v3, s2, v0
	v_and_b32_e32 v4, 4, v4
	v_and_b32_e32 v5, 24, v5
	v_or3_b32 v0, v0, v4, v5
	v_mul_i32_i24_e32 v5, 64, v10
	v_sub_u32_e32 v2, v2, v5
	v_lshlrev_b32_e32 v4, 5, v11
	v_ashrrev_i16_sdwa v2, v216, sext(v2) dst_sel:DWORD dst_unused:UNUSED_PAD src0_sel:DWORD src1_sel:BYTE_0
	v_readlane_b32 s6, v254, 44
	v_and_b32_e32 v4, 32, v4
	v_bfe_i32 v12, v2, 0, 16
	v_readlane_b32 s7, v254, 45
	s_add_u32 s12, s90, s6
	v_add_lshl_u32 v2, v4, v12, 1
	s_addc_u32 s13, s4, s7
	s_add_i32 s87, s75, 0
	v_lshl_add_u32 v0, v0, 11, v2
	s_add_i32 m0, s87, 0x10000
	v_writelane_b32 v255, s34, 50
	global_load_lds_dwordx4 v0, s[12:13]
	s_add_i32 m0, s87, 0x12000
	v_readlane_b32 s6, v254, 51
	v_writelane_b32 v255, s35, 51
	v_lshl_add_u32 v148, v3, 11, v2
	global_load_lds_dwordx4 v138, s[12:13]
	s_mov_b32 m0, s87
	v_readlane_b32 s7, v254, 52
	s_add_i32 s34, s87, 0x2000
	s_mov_b32 s72, s84
	v_mov_b32_e32 v139, v1
	s_mov_b32 s73, s4
	v_lshl_add_u64 v[2:3], s[12:13], 0, v[0:1]
	global_load_lds_dwordx4 v148, s[6:7]
	s_mov_b32 m0, s34
	v_lshl_add_u64 v[4:5], s[12:13], 0, v[138:139]
	global_load_lds_dwordx4 v140, s[6:7]
	s_add_u32 s6, s12, 0x40000
	s_addc_u32 s7, s13, 0
	s_add_i32 m0, s87, 0x14000
	s_add_i32 s35, s87, 0x4000
	global_load_lds_dwordx4 v0, s[6:7]
	s_add_i32 m0, s87, 0x16000
	s_add_i32 s84, s87, 0x6000
	global_load_lds_dwordx4 v138, s[6:7]
	v_readlane_b32 s6, v254, 53
	s_mov_b32 m0, s35
	v_readlane_b32 s7, v254, 54
	s_cmp_lg_u32 s0, 1
	v_readlane_b32 s4, v254, 19
	v_readlane_b32 s5, v254, 20
	s_nop 1
	global_load_lds_dwordx4 v148, s[6:7]
	s_mov_b32 m0, s84
	s_nop 0
	global_load_lds_dwordx4 v140, s[6:7]
	s_cbranch_scc1 .LBB0_594
	s_setprio 1
	s_barrier
